# wide conversion routine also for the HGRN2 phase's spare-workgroup conversions (HG_OUT, NSA_IN layer 3)
# baseline (speedup 1.0000x reference)
; __device__ __forceinline__ void p0_deferred(Frame& F, int my, int nconv, int part = -1) {
;     const int gw0 = F.gw, ngw0 = F.ngw; F.gw = my * NWAVES + F.wave; F.ngw = nconv * NWAVES;
;     int it0 = 0;
;     if (part < 0 || part == 0) p0_transpose_matrix(F, FIN(F, 18), DM, DM, (bf16*)FW(F, WS_W_HG_OUT), DM / 32, [](int nb) { return nb * 32; }, it0);
;     if (part < 0 || part == 1) p0_transpose_matrix(F, FIN(F, 3) + (size_t)DM * 11360, DM, 11360, (bf16*)FW(F, WS_W_NSA_IN) + (size_t)NSA_NP * DM, NSA_NP / 32,
;         [](int nb) { const int n = nb * 32; return n < 7168 ? n : (n < 11264 ? n + 96 : (n < 11360 ? n - 4096 : -1)); }, it0, FIN(F, 1) + 3 * DM);
;     if (part < 0 || part == 2) p0_transpose_matrix(F, FIN(F, 7) + (size_t)DM * DM, DM, DM, (bf16*)FW(F, WS_W_NSA_OUT) + (size_t)DM * DM, DM / 32, [](int nb) { return nb * 32; }, it0);
;     F.gw = gw0; F.ngw = ngw0;
; }
.LBB0_1675:
	s_and_b64 vcc, exec, s[0:1]
	s_cbranch_vccz .LBB0_1776
	s_lshl_b32 s0, s40, 4
	s_add_i32 s8, s33, s0
	s_add_i32 s8, s8, -16
	v_readlane_b32 s0, v254, 7
	s_lshl_b32 s2, s8, 3
	v_readlane_b32 s1, v254, 8
	s_load_dwordx2 s[4:5], s[0:1], 0x90
	s_add_u32 s0, s70, 0x1d600000
	s_addc_u32 s1, s71, 0
	s_add_i32 s2, s90, s2
	s_addk_i32 s2, 0x400
	s_ashr_i32 s7, s2, 31
	s_lshr_b32 s7, s7, 22
	s_add_i32 s7, s2, s7
	s_lshl_b32 s6, s90, 14
	s_and_b32 s7, s7, 0xfffffc00
	s_add_i32 s6, s6, 0
	s_sub_i32 s9, s2, s7
	v_mov_b32_e32 v19, 0
	v_mov_b32_e32 v15, v19
	v_lshl_add_u32 v30, v36, 2, s6
	v_mul_u32_u24_e32 v2, 0x420, v17
	v_lshlrev_b32_e32 v3, 2, v35
	s_lshl_b32 s10, s9, 5
	s_mov_b32 s3, 0
	s_waitcnt lgkmcnt(0)
	v_lshl_add_u64 v[6:7], s[4:5], 0, v[14:15]
	v_lshl_add_u64 v[8:9], s[0:1], 0, v[18:19]
	v_add3_u32 v31, s6, v2, v3
	v_add_u32_e32 v15, 0x400, v30
	v_add_u32_e32 v17, 0x800, v30
	v_add_u32_e32 v20, 0xc00, v30
	v_add_u32_e32 v21, 0x1000, v30
	v_add_u32_e32 v22, 0x1400, v30
	v_add_u32_e32 v23, 0x1800, v30
	v_add_u32_e32 v24, 0x1c00, v30
	v_mov_b32_e32 v26, v19
	v_mov_b32_e32 v27, v19
	v_mov_b32_e32 v28, v19
	v_mov_b32_e32 v29, v19
	s_mov_b32 s11, s10
	s_mov_b32 s12, s9
	v_readlane_b32 s62, v254, 7
	v_readlane_b32 s63, v254, 8
	s_nop 3
	s_load_dwordx2 s[44:45], s[62:63], 0x90
	s_waitcnt lgkmcnt(0)
	s_mov_b64 s[52:53], 0
	s_mov_b32 s46, 0x4000
	s_mov_b32 s47, 0
	s_add_u32 s48, s70, 0x1d600000
	s_addc_u32 s49, s71, 0
	s_mov_b32 s50, 32
	s_mov_b32 s51, 0x20
	s_mov_b32 s54, 0
	s_mov_b32 s55, 0
	s_lshl_b32 s56, s8, 3
	s_add_i32 s56, s56, s90
	s_mov_b32 s32, 5
	s_branch .Lcvb_run
.Lcv_ret5:
.LBB0_1688:
	s_waitcnt vmcnt(0)
	s_mov_b32 s3, 0
	v_cmp_eq_u32_e32 vcc, 0, v216
	s_waitcnt vmcnt(0)
	s_barrier
	s_and_saveexec_b64 s[4:5], vcc
	s_cbranch_execz .LBB0_1691
	s_mov_b64 s[6:7], exec
	v_mbcnt_lo_u32_b32 v2, s6, 0
	buffer_wbl2 sc1
	s_waitcnt vmcnt(0)
	v_mbcnt_hi_u32_b32 v2, s7, v2
	v_cmp_eq_u32_e32 vcc, 0, v2
	s_and_b64 s[12:13], exec, vcc
	s_mov_b64 exec, s[12:13]
	s_cbranch_execz .LBB0_1691
	s_bcnt1_i32_b64 s2, s[6:7]
	v_mov_b32_e32 v2, 0
	v_mov_b32_e32 v3, s2
	global_atomic_add v2, v3, s[70:71] offset:768
.LBB0_1691:
	s_or_b64 exec, exec, s[4:5]
	v_readlane_b32 s6, v254, 7
	v_readlane_b32 s7, v254, 8
	s_load_dwordx2 s[4:5], s[6:7], 0x8
	s_nop 0
	s_load_dwordx2 s[6:7], s[6:7], 0x18
	v_lshlrev_b32_e32 v2, 2, v16
	v_mov_b32_e32 v3, 0
	v_mov_b32_e32 v15, v3
	s_waitcnt lgkmcnt(0)
	v_lshl_add_u64 v[4:5], s[4:5], 0, v[2:3]
	s_mov_b64 s[4:5], 0xc000
	v_lshlrev_b32_e32 v2, 1, v16
	v_lshl_add_u64 v[18:19], v[4:5], 0, s[4:5]
	v_lshl_add_u64 v[4:5], s[70:71], 0, v[2:3]
	s_mov_b64 s[4:5], 0x5c00000
	v_lshl_add_u64 v[20:21], v[4:5], 0, s[4:5]
	v_lshl_add_u64 v[4:5], s[6:7], 0, v[14:15]
	s_mov_b64 s[4:5], 0xb180000
	v_lshl_add_u64 v[22:23], v[4:5], 0, s[4:5]
	s_mov_b32 s11, 0xb180
	v_add_u32_e32 v32, 0x400, v30
	v_add_u32_e32 v33, 0x800, v30
	v_add_u32_e32 v36, 0xc00, v30
	v_add_u32_e32 v37, 0x1000, v30
	v_add_u32_e32 v38, 0x1400, v30
	v_add_u32_e32 v39, 0x1800, v30
	v_add_u32_e32 v40, 0x1c00, v30
	v_mov_b32_e32 v2, v3
	v_mov_b32_e32 v4, v3
	v_mov_b32_e32 v5, v3
	v_readlane_b32 s62, v254, 7
	v_readlane_b32 s63, v254, 8
	s_nop 3
	s_load_dwordx2 s[44:45], s[62:63], 0x18
	s_load_dwordx2 s[52:53], s[62:63], 0x8
	s_waitcnt lgkmcnt(0)
	s_add_u32 s44, s44, 0xb180000
	s_addc_u32 s45, s45, 0
	s_add_u32 s52, s52, 0xc000
	s_addc_u32 s53, s53, 0
	s_mov_b32 s46, 0xb180
	s_mov_b32 s47, 1
	s_add_u32 s48, s70, 0x5c00000
	s_addc_u32 s49, s71, 0
	s_mov_b32 s50, 90
	s_mov_b32 s51, 0x22000b
	s_mov_b32 s54, 0
	s_mov_b32 s55, 0
	s_lshl_b32 s56, s8, 3
	s_add_i32 s56, s56, s90
	s_mov_b32 s32, 6
	s_branch .Lcvb_run
.Lcv_ret6:
	s_branch .LBB0_1709

; __device__ __forceinline__ void p0_deferred(Frame& F, int my, int nconv, int part = -1) {
;     const int gw0 = F.gw, ngw0 = F.ngw; F.gw = my * NWAVES + F.wave; F.ngw = nconv * NWAVES;
;     int it0 = 0;
;     if (part < 0 || part == 0) p0_transpose_matrix(F, FIN(F, 18), DM, DM, (bf16*)FW(F, WS_W_HG_OUT), DM / 32, [](int nb) { return nb * 32; }, it0);
;     if (part < 0 || part == 1) p0_transpose_matrix(F, FIN(F, 3) + (size_t)DM * 11360, DM, 11360, (bf16*)FW(F, WS_W_NSA_IN) + (size_t)NSA_NP * DM, NSA_NP / 32,
;         [](int nb) { const int n = nb * 32; return n < 7168 ? n : (n < 11264 ? n + 96 : (n < 11360 ? n - 4096 : -1)); }, it0, FIN(F, 1) + 3 * DM);
;     if (part < 0 || part == 2) p0_transpose_matrix(F, FIN(F, 7) + (size_t)DM * DM, DM, DM, (bf16*)FW(F, WS_W_NSA_OUT) + (size_t)DM * DM, DM / 32, [](int nb) { return nb * 32; }, it0);
;     F.gw = gw0; F.ngw = ngw0;
; }
.Lcvb_exit:
	s_waitcnt vmcnt(0)
	s_cmp_eq_u32 s32, 5
	s_cbranch_scc1 .Lcv_ret5
	s_branch .Lcv_ret6
